# P3 prefetch block moved from trip top to after the first barrier of the trip
# baseline (speedup 1.0000x reference)
;     __device__ __forceinline__ void operator()(const f32x4 (&acc)[2][2][4][2], const Unit& u, int wr, int wc, int fr, int fq) const {
;     ...
;         for (int g = 0; g < 8; ++g) { if constexpr (HAS_RS2) r2[g] = __hip_atomic_load(rs2 + row0 + (g >> 2) * HALF + (g & 3) * 16, __ATOMIC_RELAXED, __HIP_MEMORY_SCOPE_AGENT); else if constexpr (HAS_NRM) r2[g] = ssq[NRM_OFF + rown + (g >> 2) * HALF + (g & 3) * 16]; else r2[g] = 0.f; }
;         u32x2 raw[8][2][2];
;         if constexpr (BASEB) {
; #pragma unroll
;             for (int g = 0; g < 4; ++g)
; #pragma unroll
;                 for (int bj = 0; bj < 2; ++bj)
; #pragma unroll
;                     for (int n = 0; n < 2; ++n) raw[g][bj][n] = *(const u32x2*)((const bf16_t*)base + (size_t)(row0 + (g >> 2) * HALF + (g & 3) * 16) * 2048 + col0 + bj * HALF + n * 16);
.LBB0_651:
	ds_read_b128 v[140:143], v197
	ds_read_b128 v[144:147], v197 offset:1024
	ds_read_b128 v[148:151], v197 offset:2048
	ds_read_b128 v[152:155], v197 offset:3072
	ds_read_b128 v[156:159], v198
	ds_read_b128 v[160:163], v198 offset:1024
	ds_read_b128 v[164:167], v198 offset:2048
	ds_read_b128 v[168:171], v198 offset:3072
	s_add_u32 s28, s26, 0xfff80080
	s_addc_u32 s29, s27, -1
	s_cmp_eq_u32 s46, 28
	s_cselect_b32 s31, s15, s29
	s_cselect_b32 s30, s23, s28
	s_cselect_b32 s29, s13, s45
	s_cselect_b32 s28, s43, s44
	s_add_i32 m0, s25, 0xc000
	ds_read_b128 v[172:175], v199
	ds_read_b128 v[176:179], v199 offset:1024
	ds_read_b128 v[180:183], v199 offset:2048
	ds_read_b128 v[184:187], v199 offset:3072
	ds_read_b128 v[188:191], v199 offset:4096
	ds_read_b128 v[202:205], v199 offset:5120
	ds_read_b128 v[206:209], v199 offset:6144
	ds_read_b128 v[210:213], v199 offset:7168
	global_load_lds_dwordx4 v134, s[26:27]
	s_add_i32 m0, s25, 0xe000
	s_nop 0
	global_load_lds_dwordx4 v136, s[26:27]
	s_waitcnt vmcnt(8) lgkmcnt(0)
	s_barrier
	s_cmp_eq_u32 s46, 24
	s_cbranch_scc0 .Lp3pf_skip
	v_lshl_add_u32 v230, s24, 8, v1
	v_lshl_or_b32 v232, s22, 8, v196
	v_ashrrev_i32_e32 v233, 31, v232
	v_lshlrev_b64 v[232:233], 1, v[232:233]
	v_ashrrev_i32_e32 v231, 31, v230
	v_lshl_add_u64 v[216:217], v[230:231], 2, s[6:7]
	s_mov_b64 s[40:41], 0x20000
	v_lshlrev_b64 v[230:231], 12, v[230:231]
	v_lshl_add_u64 v[216:217], v[216:217], 0, s[40:41]
	v_lshl_add_u64 v[232:233], s[90:91], 0, v[232:233]
	v_lshl_add_u64 v[230:231], v[232:233], 0, v[230:231]
	global_load_dword v131, v[216:217], off
	global_load_dword v133, v[216:217], off offset:64
	global_load_dword v135, v[216:217], off offset:128
	global_load_dword v137, v[216:217], off offset:192
	global_load_dword v243, v[216:217], off offset:512
	s_mov_b64 s[40:41], 0x80000
	v_lshl_add_u64 v[232:233], v[230:231], 0, s[40:41]
	global_load_dwordx2 v[214:215], v[230:231], off offset:32
	global_load_dwordx2 v[218:219], v[230:231], off offset:256
	global_load_dwordx2 v[220:221], v[230:231], off offset:288
	global_load_dwordx2 v[216:217], v[230:231], off
	global_load_dwordx2 v[222:223], v[232:233], off
	global_load_dwordx2 v[224:225], v[232:233], off offset:32
	global_load_dwordx2 v[226:227], v[232:233], off offset:256
	global_load_dwordx2 v[228:229], v[232:233], off offset:288
	s_mov_b64 s[40:41], 0x10000
	v_lshl_add_u64 v[232:233], v[230:231], 0, s[40:41]
	global_load_dwordx2 v[234:235], v[232:233], off
	global_load_dwordx2 v[236:237], v[232:233], off offset:32
	global_load_dwordx2 v[238:239], v[232:233], off offset:256
	global_load_dwordx2 v[240:241], v[232:233], off offset:288
	s_mov_b64 s[40:41], 0x20000
	v_lshl_add_u64 v[232:233], v[230:231], 0, s[40:41]
	global_load_dwordx2 v[244:245], v[232:233], off
	global_load_dwordx2 v[246:247], v[232:233], off offset:32
	global_load_dwordx2 v[248:249], v[232:233], off offset:256
	global_load_dwordx2 v[250:251], v[232:233], off offset:288
	s_mov_b64 s[40:41], 0x30000
	v_lshl_add_u64 v[232:233], v[230:231], 0, s[40:41]
	global_load_dwordx2 v[252:253], v[232:233], off
	global_load_dwordx2 v[254:255], v[232:233], off offset:32
	global_load_dwordx2 v[230:231], v[232:233], off offset:256
	s_nop 0
	global_load_dwordx2 v[232:233], v[232:233], off offset:288
.Lp3pf_skip:
	v_mfma_f32_16x16x32_bf16 v[126:129], v[140:143], v[172:175], v[126:129]
	v_mfma_f32_16x16x32_bf16 v[122:125], v[148:151], v[172:175], v[122:125]
	v_mfma_f32_16x16x32_bf16 v[110:113], v[140:143], v[180:183], v[110:113]
	v_mfma_f32_16x16x32_bf16 v[106:109], v[148:151], v[180:183], v[106:109]
	v_mfma_f32_16x16x32_bf16 v[94:97], v[140:143], v[188:191], v[94:97]
	v_mfma_f32_16x16x32_bf16 v[90:93], v[148:151], v[188:191], v[90:93]
	v_mfma_f32_16x16x32_bf16 v[78:81], v[140:143], v[206:209], v[78:81]
	v_mfma_f32_16x16x32_bf16 v[74:77], v[148:151], v[206:209], v[74:77]
	v_mfma_f32_16x16x32_bf16 v[126:129], v[144:147], v[176:179], v[126:129]
	v_mfma_f32_16x16x32_bf16 v[122:125], v[152:155], v[176:179], v[122:125]
	v_mfma_f32_16x16x32_bf16 v[110:113], v[144:147], v[184:187], v[110:113]
	v_mfma_f32_16x16x32_bf16 v[106:109], v[152:155], v[184:187], v[106:109]
	v_mfma_f32_16x16x32_bf16 v[94:97], v[144:147], v[202:205], v[94:97]
	v_mfma_f32_16x16x32_bf16 v[90:93], v[152:155], v[202:205], v[90:93]
	v_mfma_f32_16x16x32_bf16 v[78:81], v[144:147], v[210:213], v[78:81]
	v_mfma_f32_16x16x32_bf16 v[74:77], v[152:155], v[210:213], v[74:77]
	v_mfma_f32_16x16x32_bf16 v[118:121], v[156:159], v[172:175], v[118:121]
	v_mfma_f32_16x16x32_bf16 v[114:117], v[164:167], v[172:175], v[114:117]
	v_mfma_f32_16x16x32_bf16 v[102:105], v[156:159], v[180:183], v[102:105]
	v_mfma_f32_16x16x32_bf16 v[98:101], v[164:167], v[180:183], v[98:101]
	v_mfma_f32_16x16x32_bf16 v[86:89], v[156:159], v[188:191], v[86:89]
	v_mfma_f32_16x16x32_bf16 v[82:85], v[164:167], v[188:191], v[82:85]
	v_mfma_f32_16x16x32_bf16 v[70:73], v[156:159], v[206:209], v[70:73]
	v_mfma_f32_16x16x32_bf16 v[66:69], v[164:167], v[206:209], v[66:69]
	v_mfma_f32_16x16x32_bf16 v[118:121], v[160:163], v[176:179], v[118:121]
	v_mfma_f32_16x16x32_bf16 v[114:117], v[168:171], v[176:179], v[114:117]
	v_mfma_f32_16x16x32_bf16 v[102:105], v[160:163], v[184:187], v[102:105]
	v_mfma_f32_16x16x32_bf16 v[98:101], v[168:171], v[184:187], v[98:101]
	v_mfma_f32_16x16x32_bf16 v[86:89], v[160:163], v[202:205], v[86:89]
	v_mfma_f32_16x16x32_bf16 v[82:85], v[168:171], v[202:205], v[82:85]
	v_mfma_f32_16x16x32_bf16 v[70:73], v[160:163], v[210:213], v[70:73]
	v_mfma_f32_16x16x32_bf16 v[66:69], v[168:171], v[210:213], v[66:69]
	s_barrier
	s_add_i32 m0, s3, 0x10000
	ds_read_b128 v[172:175], v199 offset:16384
	ds_read_b128 v[176:179], v199 offset:17408
	ds_read_b128 v[180:183], v199 offset:18432
	ds_read_b128 v[184:187], v199 offset:19456
	ds_read_b128 v[188:191], v199 offset:20480
	ds_read_b128 v[202:205], v199 offset:21504
	ds_read_b128 v[206:209], v199 offset:22528
	ds_read_b128 v[210:213], v199 offset:23552
	global_load_lds_dwordx4 v130, s[28:29]
	s_add_i32 m0, s3, 0x12000
	s_add_u32 s48, s28, 0x80000
	s_addc_u32 s49, s29, 0
	global_load_lds_dwordx4 v132, s[28:29]
	s_add_i32 m0, s3, 0x14000
	s_nop 0
	global_load_lds_dwordx4 v130, s[48:49]
	s_add_i32 m0, s3, 0x16000
	s_nop 0
	global_load_lds_dwordx4 v132, s[48:49]
	s_mov_b32 m0, s25
	s_nop 0
	global_load_lds_dwordx4 v130, s[30:31]
	s_mov_b32 m0, s34
	s_nop 0
	global_load_lds_dwordx4 v132, s[30:31]
	s_waitcnt vmcnt(8) lgkmcnt(0)
	s_barrier
	v_mfma_f32_16x16x32_bf16 v[62:65], v[140:143], v[172:175], v[62:65]
	v_mfma_f32_16x16x32_bf16 v[58:61], v[148:151], v[172:175], v[58:61]
	v_mfma_f32_16x16x32_bf16 v[46:49], v[140:143], v[180:183], v[46:49]
	v_mfma_f32_16x16x32_bf16 v[42:45], v[148:151], v[180:183], v[42:45]
	v_mfma_f32_16x16x32_bf16 v[30:33], v[140:143], v[188:191], v[30:33]
	v_mfma_f32_16x16x32_bf16 v[26:29], v[148:151], v[188:191], v[26:29]
	v_mfma_f32_16x16x32_bf16 v[14:17], v[140:143], v[206:209], v[14:17]
	v_mfma_f32_16x16x32_bf16 v[10:13], v[148:151], v[206:209], v[10:13]
	v_mfma_f32_16x16x32_bf16 v[62:65], v[144:147], v[176:179], v[62:65]
	v_mfma_f32_16x16x32_bf16 v[58:61], v[152:155], v[176:179], v[58:61]
	v_mfma_f32_16x16x32_bf16 v[46:49], v[144:147], v[184:187], v[46:49]
	v_mfma_f32_16x16x32_bf16 v[42:45], v[152:155], v[184:187], v[42:45]
	v_mfma_f32_16x16x32_bf16 v[30:33], v[144:147], v[202:205], v[30:33]
	v_mfma_f32_16x16x32_bf16 v[26:29], v[152:155], v[202:205], v[26:29]
	v_mfma_f32_16x16x32_bf16 v[14:17], v[144:147], v[210:213], v[14:17]
	v_mfma_f32_16x16x32_bf16 v[10:13], v[152:155], v[210:213], v[10:13]
	v_mfma_f32_16x16x32_bf16 v[54:57], v[156:159], v[172:175], v[54:57]
	v_mfma_f32_16x16x32_bf16 v[50:53], v[164:167], v[172:175], v[50:53]
	v_mfma_f32_16x16x32_bf16 v[38:41], v[156:159], v[180:183], v[38:41]
	v_mfma_f32_16x16x32_bf16 v[34:37], v[164:167], v[180:183], v[34:37]
	v_mfma_f32_16x16x32_bf16 v[22:25], v[156:159], v[188:191], v[22:25]
	v_mfma_f32_16x16x32_bf16 v[18:21], v[164:167], v[188:191], v[18:21]
	v_mfma_f32_16x16x32_bf16 v[6:9], v[156:159], v[206:209], v[6:9]
	v_mfma_f32_16x16x32_bf16 v[2:5], v[164:167], v[206:209], v[2:5]
	v_mfma_f32_16x16x32_bf16 v[54:57], v[160:163], v[176:179], v[54:57]
	v_mfma_f32_16x16x32_bf16 v[50:53], v[168:171], v[176:179], v[50:53]
	v_mfma_f32_16x16x32_bf16 v[38:41], v[160:163], v[184:187], v[38:41]
	v_mfma_f32_16x16x32_bf16 v[34:37], v[168:171], v[184:187], v[34:37]
	v_mfma_f32_16x16x32_bf16 v[22:25], v[160:163], v[202:205], v[22:25]
	v_mfma_f32_16x16x32_bf16 v[18:21], v[168:171], v[202:205], v[18:21]
	v_mfma_f32_16x16x32_bf16 v[6:9], v[160:163], v[210:213], v[6:9]
	v_mfma_f32_16x16x32_bf16 v[2:5], v[168:171], v[210:213], v[2:5]
	s_barrier
	ds_read_b128 v[140:143], v192
	ds_read_b128 v[144:147], v192 offset:1024
	ds_read_b128 v[148:151], v192 offset:2048
	ds_read_b128 v[152:155], v192 offset:3072
	ds_read_b128 v[156:159], v193
	ds_read_b128 v[160:163], v193 offset:1024
	ds_read_b128 v[164:167], v193 offset:2048
	ds_read_b128 v[168:171], v193 offset:3072
	s_add_u32 s30, s30, 0x80000
	s_addc_u32 s31, s31, 0
	s_mov_b32 m0, s35
	ds_read_b128 v[172:175], v199 offset:32768
	ds_read_b128 v[176:179], v199 offset:33792
	ds_read_b128 v[180:183], v199 offset:34816
	ds_read_b128 v[184:187], v199 offset:35840
	ds_read_b128 v[188:191], v199 offset:36864
	ds_read_b128 v[202:205], v199 offset:37888
	ds_read_b128 v[206:209], v199 offset:38912
	ds_read_b128 v[210:213], v199 offset:39936
	global_load_lds_dwordx4 v130, s[30:31]
	s_mov_b32 m0, s36
	s_nop 0
	global_load_lds_dwordx4 v132, s[30:31]
	s_waitcnt vmcnt(8) lgkmcnt(0)
	s_barrier
	v_mfma_f32_16x16x32_bf16 v[126:129], v[140:143], v[172:175], v[126:129]
	v_mfma_f32_16x16x32_bf16 v[122:125], v[148:151], v[172:175], v[122:125]
	v_mfma_f32_16x16x32_bf16 v[110:113], v[140:143], v[180:183], v[110:113]
	v_mfma_f32_16x16x32_bf16 v[106:109], v[148:151], v[180:183], v[106:109]
	v_mfma_f32_16x16x32_bf16 v[94:97], v[140:143], v[188:191], v[94:97]
	v_mfma_f32_16x16x32_bf16 v[90:93], v[148:151], v[188:191], v[90:93]
	v_mfma_f32_16x16x32_bf16 v[78:81], v[140:143], v[206:209], v[78:81]
	v_mfma_f32_16x16x32_bf16 v[74:77], v[148:151], v[206:209], v[74:77]
	v_mfma_f32_16x16x32_bf16 v[126:129], v[144:147], v[176:179], v[126:129]
	v_mfma_f32_16x16x32_bf16 v[122:125], v[152:155], v[176:179], v[122:125]
	v_mfma_f32_16x16x32_bf16 v[110:113], v[144:147], v[184:187], v[110:113]
	v_mfma_f32_16x16x32_bf16 v[106:109], v[152:155], v[184:187], v[106:109]
	v_mfma_f32_16x16x32_bf16 v[94:97], v[144:147], v[202:205], v[94:97]
	v_mfma_f32_16x16x32_bf16 v[90:93], v[152:155], v[202:205], v[90:93]
	v_mfma_f32_16x16x32_bf16 v[78:81], v[144:147], v[210:213], v[78:81]
	v_mfma_f32_16x16x32_bf16 v[74:77], v[152:155], v[210:213], v[74:77]
	v_mfma_f32_16x16x32_bf16 v[118:121], v[156:159], v[172:175], v[118:121]
	v_mfma_f32_16x16x32_bf16 v[114:117], v[164:167], v[172:175], v[114:117]
	v_mfma_f32_16x16x32_bf16 v[102:105], v[156:159], v[180:183], v[102:105]
	v_mfma_f32_16x16x32_bf16 v[98:101], v[164:167], v[180:183], v[98:101]
	v_mfma_f32_16x16x32_bf16 v[86:89], v[156:159], v[188:191], v[86:89]
	v_mfma_f32_16x16x32_bf16 v[82:85], v[164:167], v[188:191], v[82:85]
	v_mfma_f32_16x16x32_bf16 v[70:73], v[156:159], v[206:209], v[70:73]
	v_mfma_f32_16x16x32_bf16 v[66:69], v[164:167], v[206:209], v[66:69]
	v_mfma_f32_16x16x32_bf16 v[118:121], v[160:163], v[176:179], v[118:121]
	v_mfma_f32_16x16x32_bf16 v[114:117], v[168:171], v[176:179], v[114:117]
	v_mfma_f32_16x16x32_bf16 v[102:105], v[160:163], v[184:187], v[102:105]
	v_mfma_f32_16x16x32_bf16 v[98:101], v[168:171], v[184:187], v[98:101]
	v_mfma_f32_16x16x32_bf16 v[86:89], v[160:163], v[202:205], v[86:89]
	v_mfma_f32_16x16x32_bf16 v[82:85], v[168:171], v[202:205], v[82:85]
	v_mfma_f32_16x16x32_bf16 v[70:73], v[160:163], v[210:213], v[70:73]
	v_mfma_f32_16x16x32_bf16 v[66:69], v[168:171], v[210:213], v[66:69]
	s_barrier
	s_add_u32 s98, s30, 0xfff80080
	s_addc_u32 s99, s31, -1
	s_add_i32 m0, s3, 0x18000
	ds_read_b128 v[172:175], v199 offset:49152
	ds_read_b128 v[176:179], v199 offset:50176
	ds_read_b128 v[180:183], v199 offset:51200
	ds_read_b128 v[184:187], v199 offset:52224
	ds_read_b128 v[188:191], v199 offset:53248
	ds_read_b128 v[202:205], v199 offset:54272
	ds_read_b128 v[206:209], v199 offset:55296
	ds_read_b128 v[210:213], v199 offset:56320
	s_add_u32 s100, s28, 0x80
	s_addc_u32 s101, s29, 0
	global_load_lds_dwordx4 v130, s[100:101]
	s_add_i32 m0, s3, 0x1a000
	s_add_u32 s28, s28, 0x80080
	s_addc_u32 s29, s29, 0
	global_load_lds_dwordx4 v132, s[100:101]
	s_add_i32 m0, s3, 0x1c000
	s_nop 0
	global_load_lds_dwordx4 v130, s[28:29]
	s_add_i32 m0, s3, 0x1e000
	s_nop 0
	global_load_lds_dwordx4 v132, s[28:29]
	s_mov_b32 m0, s38
	s_nop 0
	global_load_lds_dwordx4 v130, s[98:99]
	s_mov_b32 m0, s39
	s_nop 0
	global_load_lds_dwordx4 v132, s[98:99]
	s_waitcnt vmcnt(8) lgkmcnt(0)
	s_barrier
	v_mfma_f32_16x16x32_bf16 v[62:65], v[140:143], v[172:175], v[62:65]
	v_mfma_f32_16x16x32_bf16 v[58:61], v[148:151], v[172:175], v[58:61]
	v_mfma_f32_16x16x32_bf16 v[46:49], v[140:143], v[180:183], v[46:49]
	v_mfma_f32_16x16x32_bf16 v[42:45], v[148:151], v[180:183], v[42:45]
	v_mfma_f32_16x16x32_bf16 v[30:33], v[140:143], v[188:191], v[30:33]
	v_mfma_f32_16x16x32_bf16 v[26:29], v[148:151], v[188:191], v[26:29]
	v_mfma_f32_16x16x32_bf16 v[14:17], v[140:143], v[206:209], v[14:17]
	v_mfma_f32_16x16x32_bf16 v[10:13], v[148:151], v[206:209], v[10:13]
	v_mfma_f32_16x16x32_bf16 v[62:65], v[144:147], v[176:179], v[62:65]
	v_mfma_f32_16x16x32_bf16 v[58:61], v[152:155], v[176:179], v[58:61]
	v_mfma_f32_16x16x32_bf16 v[46:49], v[144:147], v[184:187], v[46:49]
	v_mfma_f32_16x16x32_bf16 v[42:45], v[152:155], v[184:187], v[42:45]
	v_mfma_f32_16x16x32_bf16 v[30:33], v[144:147], v[202:205], v[30:33]
	v_mfma_f32_16x16x32_bf16 v[26:29], v[152:155], v[202:205], v[26:29]
	v_mfma_f32_16x16x32_bf16 v[14:17], v[144:147], v[210:213], v[14:17]
	v_mfma_f32_16x16x32_bf16 v[10:13], v[152:155], v[210:213], v[10:13]
	v_mfma_f32_16x16x32_bf16 v[54:57], v[156:159], v[172:175], v[54:57]
	v_mfma_f32_16x16x32_bf16 v[50:53], v[164:167], v[172:175], v[50:53]
	v_mfma_f32_16x16x32_bf16 v[38:41], v[156:159], v[180:183], v[38:41]
	v_mfma_f32_16x16x32_bf16 v[34:37], v[164:167], v[180:183], v[34:37]
	v_mfma_f32_16x16x32_bf16 v[22:25], v[156:159], v[188:191], v[22:25]
	v_mfma_f32_16x16x32_bf16 v[18:21], v[164:167], v[188:191], v[18:21]
	v_mfma_f32_16x16x32_bf16 v[6:9], v[156:159], v[206:209], v[6:9]
	v_mfma_f32_16x16x32_bf16 v[2:5], v[164:167], v[206:209], v[2:5]
	v_mfma_f32_16x16x32_bf16 v[54:57], v[160:163], v[176:179], v[54:57]
	v_mfma_f32_16x16x32_bf16 v[50:53], v[168:171], v[176:179], v[50:53]
	v_mfma_f32_16x16x32_bf16 v[38:41], v[160:163], v[184:187], v[38:41]
	v_mfma_f32_16x16x32_bf16 v[34:37], v[168:171], v[184:187], v[34:37]
	v_mfma_f32_16x16x32_bf16 v[22:25], v[160:163], v[202:205], v[22:25]
	v_mfma_f32_16x16x32_bf16 v[18:21], v[168:171], v[202:205], v[18:21]
	v_mfma_f32_16x16x32_bf16 v[6:9], v[160:163], v[210:213], v[6:9]
	v_mfma_f32_16x16x32_bf16 v[2:5], v[168:171], v[210:213], v[2:5]
	s_barrier
	s_add_i32 s46, s46, 2
	s_add_u32 s44, s44, 0x100
	s_addc_u32 s45, s45, 0
	s_add_u32 s26, s26, 0x100
	s_addc_u32 s27, s27, 0
	s_cmp_gt_u32 s46, 29
	s_cbranch_scc0 .LBB0_651
	s_and_b64 vcc, exec, s[10:11]
	s_cbranch_vccz .LBB0_654
	s_barrier
